# drop the now-unused per-XCD release atomic in the grid barrier; SGU LayerNorm loop issues its four row loads before the first wait
# baseline (speedup 1.0000x reference)
.LBB0_225:
	s_or_b64 exec, exec, s[34:35]
	s_mov_b64 s[34:35], exec
	v_mbcnt_lo_u32_b32 v0, s34, 0
	v_mbcnt_hi_u32_b32 v0, s35, v0
	v_cmp_eq_u32_e32 vcc, 0, v0
	s_waitcnt vmcnt(0)
	buffer_inv sc1
	s_and_saveexec_b64 s[36:37], vcc
	s_cbranch_execz .LBB0_227
	s_bcnt1_i32_b64 s19, s[34:35]
	v_mov_b32_e32 v0, s19
	s_nop 0

.LBB0_396:
	s_or_b64 exec, exec, s[26:27]
	s_mov_b64 s[26:27], exec
	v_mbcnt_lo_u32_b32 v0, s26, 0
	v_mbcnt_hi_u32_b32 v0, s27, v0
	v_cmp_eq_u32_e32 vcc, 0, v0
	s_waitcnt vmcnt(0)
	buffer_inv sc1
	s_and_saveexec_b64 s[28:29], vcc
	s_cbranch_execz .LBB0_398
	s_bcnt1_i32_b64 s2, s[26:27]
	v_mov_b32_e32 v0, s2
	s_nop 0

.LBB0_407:
	v_add_co_u32_e32 v20, vcc, 0xffffc000, v0
	s_nop 1
	v_addc_co_u32_e32 v21, vcc, -1, v1, vcc
	global_load_dwordx4 v[42:45], v[20:21], off offset:-2048
	v_add_co_u32_e32 v20, vcc, 0xffffd000, v0
	s_nop 1
	v_addc_co_u32_e32 v21, vcc, -1, v1, vcc
	global_load_dwordx4 v[28:31], v[20:21], off
	v_add_co_u32_e32 v20, vcc, 0xfffff000, v0
	s_nop 1
	v_addc_co_u32_e32 v21, vcc, -1, v1, vcc
	global_load_dwordx4 v[24:27], v[20:21], off offset:-2048
	s_nop 0
	global_load_dwordx4 v[20:23], v[0:1], off
	s_waitcnt vmcnt(3)
	v_lshlrev_b32_e32 v40, 16, v42
	v_and_b32_e32 v39, 0xffff0000, v42
	v_add_f32_e32 v41, 0, v40
	v_lshlrev_b32_e32 v38, 16, v43
	v_add_f32_e32 v41, v41, v39
	v_and_b32_e32 v37, 0xffff0000, v43
	v_add_f32_e32 v41, v41, v38
	v_lshlrev_b32_e32 v36, 16, v44
	v_add_f32_e32 v41, v41, v37
	v_and_b32_e32 v35, 0xffff0000, v44
	v_add_f32_e32 v41, v41, v36
	v_lshlrev_b32_e32 v34, 16, v45
	v_add_f32_e32 v41, v41, v35
	v_and_b32_e32 v33, 0xffff0000, v45
	v_add_f32_e32 v41, v41, v34
	v_add_f32_e32 v41, v41, v33
	v_mov_b32_e32 v42, v2
	s_nop 0
	v_add_f32_dpp v41, v41, v41 row_shr:1 row_mask:0xf bank_mask:0xf bound_ctrl:1
	s_nop 1
	v_add_f32_dpp v41, v41, v41 row_shr:2 row_mask:0xf bank_mask:0xf bound_ctrl:1
	s_nop 1
	v_add_f32_dpp v41, v41, v41 row_shr:4 row_mask:0xf bank_mask:0xf bound_ctrl:1
	s_nop 1
	v_add_f32_dpp v41, v41, v41 row_shr:8 row_mask:0xf bank_mask:0xf bound_ctrl:1
	s_nop 1
	v_mov_b32_dpp v42, v41 row_bcast:15 row_mask:0xa bank_mask:0xf
	v_add_f32_e32 v41, v41, v42
	v_mov_b32_e32 v42, v2
	s_nop 1
	v_mov_b32_dpp v42, v41 row_bcast:31 row_mask:0xc bank_mask:0xf
	v_add_f32_e32 v41, v41, v42
	v_mov_b32_e32 v42, v2
	v_readlane_b32 s34, v41, 63
	s_nop 1
	v_fmac_f32_e32 v39, s34, v222
	v_fmac_f32_e32 v40, s34, v222
	v_mul_f32_e32 v41, v39, v39
	v_fmac_f32_e32 v41, v40, v40
	v_fmac_f32_e32 v38, s34, v222
	v_fmac_f32_e32 v41, v38, v38
	v_fmac_f32_e32 v37, s34, v222
	v_fmac_f32_e32 v41, v37, v37
	v_fmac_f32_e32 v36, s34, v222
	v_fmac_f32_e32 v41, v36, v36
	v_fmac_f32_e32 v35, s34, v222
	v_fmac_f32_e32 v41, v35, v35
	v_fmac_f32_e32 v34, s34, v222
	v_fmac_f32_e32 v41, v34, v34
	v_fmac_f32_e32 v33, s34, v222
	v_fmac_f32_e32 v41, v33, v33
	s_nop 1
	v_add_f32_dpp v41, v41, v41 row_shr:1 row_mask:0xf bank_mask:0xf bound_ctrl:1
	s_nop 1
	v_add_f32_dpp v41, v41, v41 row_shr:2 row_mask:0xf bank_mask:0xf bound_ctrl:1
	s_nop 1
	v_add_f32_dpp v41, v41, v41 row_shr:4 row_mask:0xf bank_mask:0xf bound_ctrl:1
	s_nop 1
	v_add_f32_dpp v41, v41, v41 row_shr:8 row_mask:0xf bank_mask:0xf bound_ctrl:1
	s_nop 1
	v_mov_b32_dpp v42, v41 row_bcast:15 row_mask:0xa bank_mask:0xf
	v_add_f32_e32 v41, v41, v42
	v_mov_b32_e32 v42, v2
	s_nop 1
	v_mov_b32_dpp v42, v41 row_bcast:31 row_mask:0xc bank_mask:0xf
	v_add_f32_e32 v41, v41, v42
	s_nop 0
	v_readlane_b32 s40, v41, 63
	s_and_saveexec_b64 s[34:35], s[38:39]
	s_cbranch_execz .LBB0_409
	v_fma_f32 v41, s40, v223, v159
	v_rsq_f32_e32 v41, v41
	s_nop 0
	v_mul_f32_e32 v40, v40, v41
	v_mul_f32_e32 v39, v39, v41
	v_mul_f32_e32 v38, v38, v41
	v_mul_f32_e32 v37, v37, v41
	v_mul_f32_e32 v36, v36, v41
	v_mul_f32_e32 v35, v35, v41
	v_mul_f32_e32 v34, v34, v41
	v_mul_f32_e32 v33, v33, v41
	v_fma_f32 v40, v4, v40, v12
	v_fma_f32 v39, v5, v39, v13
	v_fma_f32 v38, v6, v38, v14
	v_fma_f32 v37, v7, v37, v15
	v_fma_f32 v36, v8, v36, v16
	v_fma_f32 v35, v9, v35, v17
	v_fma_f32 v34, v10, v34, v18
	v_fma_f32 v33, v11, v33, v19
	v_cvt_pk_bf16_f32 v40, v40, v2
	ds_write_b16 v32, v40
	v_cvt_pk_bf16_f32 v39, v39, v2
	ds_write_b16 v32, v39 offset:272
	v_cvt_pk_bf16_f32 v38, v38, v2
	ds_write_b16 v32, v38 offset:544
	v_cvt_pk_bf16_f32 v37, v37, v2
	ds_write_b16 v32, v37 offset:816
	v_cvt_pk_bf16_f32 v36, v36, v2
	ds_write_b16 v32, v36 offset:1088
	v_cvt_pk_bf16_f32 v35, v35, v2
	ds_write_b16 v32, v35 offset:1360
	v_cvt_pk_bf16_f32 v34, v34, v2
	ds_write_b16 v32, v34 offset:1632
	v_cvt_pk_bf16_f32 v33, v33, v2
	ds_write_b16 v32, v33 offset:1904

.LBB0_540:
	s_or_b64 exec, exec, s[22:23]
	s_mov_b64 s[22:23], exec
	v_mbcnt_lo_u32_b32 v0, s22, 0
	v_mbcnt_hi_u32_b32 v0, s23, v0
	v_cmp_eq_u32_e32 vcc, 0, v0
	s_waitcnt vmcnt(0)
	buffer_inv sc1
	s_and_saveexec_b64 s[28:29], vcc
	s_cbranch_execz .LBB0_542
	s_bcnt1_i32_b64 s2, s[22:23]
	v_mov_b32_e32 v0, s2
	s_nop 0

.LBB0_631:
	s_or_b64 exec, exec, s[20:21]
	s_mov_b64 s[20:21], exec
	v_mbcnt_lo_u32_b32 v0, s20, 0
	v_mbcnt_hi_u32_b32 v0, s21, v0
	v_cmp_eq_u32_e32 vcc, 0, v0
	s_waitcnt vmcnt(0)
	buffer_inv sc1
	s_and_saveexec_b64 s[22:23], vcc
	s_cbranch_execz .LBB0_152
	s_bcnt1_i32_b64 s2, s[20:21]
	v_mov_b32_e32 v0, s2
	s_nop 0
	s_branch .LBB0_152
